# speedup vs baseline: 1.0340x; 1.0340x over previous
.LBB0_180:
	s_waitcnt lgkmcnt(0)
	s_barrier
	s_cmpk_lt_i32 s99, 0x500
	s_cbranch_scc1 .Lsig_done
	s_waitcnt vmcnt(0)
	s_barrier
	v_cmp_eq_u32_e32 vcc, 0, v208
	s_and_b64 exec, exec, vcc
	s_cbranch_execz .Lsig_restore
	v_readlane_b32 s100, v254, 2
	v_readlane_b32 s101, v254, 3
	v_readlane_b32 vcc_lo, v254, 28
	s_nop 1
	s_cmpk_lt_i32 s99, 0x600
	s_cbranch_scc0 .Lsig_k6
	v_mov_b32_e32 v0, 0x200f0
	ds_read_b32 v0, v0
	s_lshl_b32 vcc_lo, vcc_lo, 5
	s_addk_i32 vcc_lo, 0x3e40
	s_add_u32 s100, s100, vcc_lo
	s_addc_u32 s101, s101, 0
	s_waitcnt lgkmcnt(0)
	v_and_b32_e32 v0, 7, v0
	v_lshlrev_b32_e32 v0, 2, v0
	s_nop 1
	global_atomic_add v0, v209, s[100:101]
	s_branch .Lsig_restore
.Lsig_k6:
	buffer_wbl2 sc1
	s_waitcnt vmcnt(0)
	s_lshl_b32 vcc_lo, vcc_lo, 3
	s_addk_i32 vcc_lo, 0x3e04
	s_add_u32 s100, s100, vcc_lo
	s_addc_u32 s101, s101, 0
	s_nop 4
	global_atomic_add v175, v209, s[100:101]

.LBB0_285:
	s_waitcnt vmcnt(0)
	s_barrier
	s_and_saveexec_b64 s[0:1], s[46:47]
	v_readlane_b32 s10, v254, 23
	s_mov_b64 s[12:13], 0x2000
	s_cbranch_execz .LBB0_322
	v_readlane_b32 s2, v254, 2
	v_readlane_b32 s3, v254, 3
	v_readlane_b32 s7, v254, 15
	s_lshl_b32 s4, s98, 3
	s_addk_i32 s4, 0x3e00
	s_add_u32 s8, s2, s4
	s_addc_u32 s9, s3, 0
	s_cmpk_lt_i32 s7, 0x80
	s_cbranch_scc1 .Lw1_global
	v_mov_b32_e32 v0, 0x200f0
	ds_read_b64 v[0:1], v0
	s_lshl_b32 s4, s98, 5
	s_addk_i32 s4, 0x3e40
	s_add_u32 s2, s2, s4
	s_addc_u32 s3, s3, 0
	s_mov_b32 s4, 0
	s_waitcnt lgkmcnt(0)
	v_readfirstlane_b32 s6, v1
	v_and_b32_e32 v0, 7, v0
	v_lshlrev_b32_e32 v2, 2, v0
	s_nop 1
.Lw1_xspin:
	global_load_dword v0, v2, s[2:3] sc1
	s_waitcnt vmcnt(0)
	v_readfirstlane_b32 s5, v0
	s_cmp_lt_u32 s5, s6
	s_cbranch_scc0 .Lw1_xdone
	s_add_i32 s4, s4, 1
	s_cmp_lt_u32 s4, 0x40000
	s_cbranch_scc0 .Lw1_xdone
	s_sleep 2
	s_branch .Lw1_xspin
.Lw1_xdone:
	buffer_wbl2 sc1
	s_waitcnt vmcnt(0)
	global_atomic_add v175, v209, s[8:9]
.Lw1_global:
	s_mov_b32 s4, 0
.Lw1_spin:
	global_load_dwordx2 v[0:1], v175, s[8:9] sc1
	s_waitcnt vmcnt(0)
	v_readfirstlane_b32 s5, v0
	v_readfirstlane_b32 s6, v1
	s_cmpk_lt_u32 s5, 0x80
	s_cbranch_scc1 .Lw1_again
	s_branch .Lw1_done
.Lw1_again:
	s_add_i32 s4, s4, 1
	s_cmp_lt_u32 s4, 0x40000
	s_cbranch_scc0 .Lw1_done
	s_sleep 2
	s_branch .Lw1_spin

.LBB0_322:
	s_or_b64 exec, exec, s[0:1]
	v_mov_b32_e32 v0, 0x20000
	s_barrier
	s_and_b32 s2, s98, 1
	v_add_u32_e32 v4, 0, v0
	ds_read_b64 v[6:7], v4 offset:216
	ds_read2_b64 v[0:3], v4 offset0:17 offset1:18
	s_mov_b32 s21, s57
	s_waitcnt lgkmcnt(0)
	v_readfirstlane_b32 s100, v6
	v_readfirstlane_b32 s101, v7
	s_nop 1
	s_sub_u32 s100, s100, 0xbb68100
	s_subb_u32 s101, s101, 0
	v_readfirstlane_b32 s0, v1
	s_nop 1
	v_writelane_b32 v254, s0, 43
	v_readfirstlane_b32 s0, v0
	v_readfirstlane_b32 s4, v3
	v_readfirstlane_b32 s5, v2
	ds_read2_b64 v[0:3], v4 offset0:24 offset1:28
	v_writelane_b32 v254, s0, 44
	s_lshl_b64 s[0:1], s[98:99], 2
	s_waitcnt lgkmcnt(0)
	v_readfirstlane_b32 s92, v2
	v_readfirstlane_b32 s93, v3
	s_add_u32 s0, s92, s0
	s_addc_u32 s1, s93, s1
	s_add_u32 s0, s0, 0xbb64040
	s_addc_u32 s1, s1, 0
	v_writelane_b32 v254, s0, 47
	s_bitcmp1_b32 s98, 0
	s_cselect_b64 s[96:97], -1, 0
	v_writelane_b32 v254, s1, 48
	s_add_u32 s0, s92, 0x20b68100
	v_writelane_b32 v254, s0, 39
	s_addc_u32 s0, s93, 0
	v_writelane_b32 v254, s0, 41
	s_add_u32 s0, s92, 0x9000000
	v_writelane_b32 v254, s0, 49
	s_addc_u32 s0, s93, 0
	v_writelane_b32 v254, s0, 50
	s_add_u32 s0, s92, 0xa000000
	v_writelane_b32 v254, s0, 51
	s_addc_u32 s0, s93, 0
	v_writelane_b32 v254, s0, 52
	s_add_u32 s0, s92, 0x22b68100
	v_writelane_b32 v254, s0, 42
	s_addc_u32 s0, s93, 0
	v_writelane_b32 v254, s0, 45
	s_add_u32 s0, s92, 0x27b68100
	v_writelane_b32 v254, s0, 53
	s_addc_u32 s0, s93, 0
	v_writelane_b32 v254, s0, 54
	s_add_u32 s0, s92, 0x24b68100
	v_writelane_b32 v254, s0, 46
	s_addc_u32 s0, s93, 0
	v_writelane_b32 v254, s0, 37
	s_and_b32 s0, s98, 2
	v_writelane_b32 v254, s0, 55
	s_add_u32 s0, s92, 0xb000000
	v_writelane_b32 v254, s0, 56
	s_addc_u32 s0, s93, 0
	v_writelane_b32 v254, s0, 57
	s_add_u32 s0, s92, 0xb400000
	v_writelane_b32 v254, s0, 58
	s_addc_u32 s0, s93, 0
	v_writelane_b32 v254, s0, 59
	s_add_u32 s0, s92, 0x26b68100
	v_writelane_b32 v254, s0, 60
	s_addc_u32 s0, s93, 0
	v_writelane_b32 v254, s0, 61
	s_add_u32 s0, s92, 0x27368100
	v_writelane_b32 v254, s0, 62
	s_addc_u32 s0, s93, 0
	v_writelane_b32 v254, s0, 63
	s_add_u32 s0, s92, 0x8800000
	v_writelane_b32 v254, s0, 31
	s_addc_u32 s0, s93, 0
	v_writelane_b32 v254, s0, 33
	s_add_u32 s0, s92, 0x8c00000
	v_writelane_b32 v254, s0, 34
	s_addc_u32 s0, s93, 0
	v_writelane_b32 v254, s0, 30
	s_lshl_b32 s0, s20, 3
	v_writelane_b32 v254, s0, 35
	s_add_u32 s0, s100, 0xbb68100
	v_writelane_b32 v254, s0, 36
	s_addc_u32 s0, s101, 0
	v_writelane_b32 v255, s0, 0
	s_lshl_b32 s0, s2, 10
	s_cmp_eq_u32 s2, 0
	v_writelane_b32 v255, s0, 1
	s_cselect_b64 s[0:1], -1, 0
	v_writelane_b32 v255, s0, 2
	v_readfirstlane_b32 s7, v0
	v_readfirstlane_b32 s6, v1
	v_writelane_b32 v255, s1, 3
	s_and_b64 s[0:1], s[0:1], exec
	s_movk_i32 s0, 0x1600
	s_cselect_b32 s0, 0x600, s0
	s_add_u32 s48, s92, 0x13b68100
	s_addc_u32 s49, s93, 0
	v_writelane_b32 v255, s0, 4
	s_add_u32 s0, s92, 0x29b68100
	s_addc_u32 s1, s93, 0
	v_writelane_b32 v255, s0, 5
	s_lshl_b32 s56, s20, 8
	v_mov_b32_e32 v0, v208
	v_writelane_b32 v255, s1, 6
	s_lshl_b64 s[0:1], s[56:57], 2
	s_add_u32 s2, s92, s0
	s_addc_u32 s3, s93, s1
	s_add_u32 s2, s2, 0xbb67700
	v_writelane_b32 v255, s2, 7
	s_addc_u32 s2, s3, 0
	v_writelane_b32 v255, s2, 8
	s_lshl_b64 s[2:3], s[20:21], 2
	s_add_u32 s2, s92, s2
	s_addc_u32 s3, s93, s3
	s_add_u32 s2, s2, 0xbb64000
	s_addc_u32 s3, s3, 0
	s_cmp_lt_u32 s98, 2
	v_writelane_b32 v255, s2, 9
	s_cselect_b64 vcc, -1, 0
	s_add_u32 s0, s7, s0
	v_writelane_b32 v255, s3, 10
	s_addc_u32 s1, s6, s1
	v_writelane_b32 v255, s0, 11
	s_mov_b32 s2, s20
	s_nop 0
	v_writelane_b32 v255, s1, 12
	v_writelane_b32 v255, s2, 13
	s_mul_i32 s1, s20, 0x3000
	s_mul_hi_u32 s0, s20, 0x3000
	v_writelane_b32 v255, s3, 14
	s_add_u32 s2, s5, s1
	s_addc_u32 s3, s4, s0
	v_writelane_b32 v255, s2, 15
	v_cmp_eq_u32_e64 s[14:15], 0, v0
	v_mov_b32_e32 v0, 0x3ee34c56
	v_writelane_b32 v255, s3, 16
	v_writelane_b32 v255, s14, 17
	v_cndmask_b32_e32 v97, v0, v219, vcc
	s_nop 0
	v_writelane_b32 v255, s15, 18
	s_mov_b32 s0, 0
	s_nop 0
	v_writelane_b32 v255, s0, 40
	s_branch .LBB0_325

.LBB0_329:
	s_or_b64 exec, exec, s[0:1]
	v_mov_b32_e32 v0, s10
	s_waitcnt lgkmcnt(0)
	s_barrier
	ds_read_b32 v0, v0
	s_mov_b64 s[0:1], -1
	s_waitcnt lgkmcnt(0)
	v_readfirstlane_b32 s6, v0
	s_cmpk_gt_i32 s6, 0x3ff
	s_cbranch_scc1 .LBB0_324
	s_cmpk_lt_i32 s6, 0x100
	s_cbranch_scc1 .Lw2_skip
	v_readlane_b32 s2, v255, 40
	s_nop 1
	s_cmp_lg_u32 s2, 0
	s_cbranch_scc1 .Lw2_skip
	s_and_saveexec_b64 vcc, s[14:15]
	s_cbranch_execz .Lw2_join
	v_readlane_b32 s2, v254, 2
	v_readlane_b32 s3, v254, 3
	v_readlane_b32 s4, v254, 28
	s_nop 1
	s_lshl_b32 s4, s4, 3
	s_addk_i32 s4, 0x3e04
	s_add_u32 s2, s2, s4
	s_addc_u32 s3, s3, 0
	s_mov_b32 s4, 0
	s_nop 4
.Lw2_spin:
	global_load_dword v0, v175, s[2:3] sc1
	s_waitcnt vmcnt(0)
	v_readfirstlane_b32 s5, v0
	s_cmpk_lt_u32 s5, 0x80
	s_cbranch_scc0 .Lw2_done
	s_add_i32 s4, s4, 1
	s_cmp_lt_u32 s4, 0x40000
	s_cbranch_scc0 .Lw2_done
	s_sleep 2
	s_branch .Lw2_spin

.Lw2_join:
	s_or_b64 exec, exec, vcc
	s_barrier
	s_mov_b32 s2, 1
	s_nop 0
	v_writelane_b32 v255, s2, 40

.LBB0_499:
	s_or_b64 exec, exec, s[6:7]
	v_mov_b32_e32 v0, s10
	s_waitcnt lgkmcnt(0)
	s_barrier
	ds_read_b32 v0, v0
	s_mov_b64 s[6:7], 0x2000
	s_waitcnt lgkmcnt(0)
	v_readfirstlane_b32 s3, v0
	s_cmp_eq_u32 s3, 0
	s_cbranch_scc1 .LBB0_502
	s_lshl_b32 s3, s4, 10
	s_addk_i32 s3, 0x2000
	s_lshl_b32 s4, s4, 8
	s_and_b64 s[0:1], s[0:1], exec
	s_cselect_b32 s4, s4, s3
	s_ashr_i32 s3, s2, 31
	s_lshl_b64 s[0:1], s[2:3], 18
	v_readlane_b32 s2, v255, 9
	v_readlane_b32 s3, v255, 10
	v_lshlrev_b32_e32 v0, 4, v6
	v_and_b32_e32 v0, 0x3f0, v0
	s_lshl_b32 s5, s12, 8
	v_ashrrev_i32_e32 v5, 1, v6
	s_add_i32 s4, s4, s5
	global_load_dword v4, v175, s[2:3]
	v_readlane_b32 s2, v255, 11
	v_readlane_b32 s3, v255, 12
	v_and_b32_e32 v12, 0xffffffe0, v5
	v_cmp_lt_i32_e32 vcc, v213, v211
	v_add_u32_e32 v14, s4, v12
	v_ashrrev_i32_e32 v15, 31, v14
	v_cndmask_b32_e32 v7, v210, v213, vcc
	global_load_dwordx4 v[0:3], v0, s[2:3]
	s_lshl_b64 s[2:3], s[56:57], 9
	s_add_u32 s2, s92, s2
	s_addc_u32 s3, s93, s3
	v_cmp_lt_i32_e32 vcc, v212, v211
	v_mov_b64_e32 v[10:11], s[2:3]
	v_ashrrev_i32_e32 v13, 31, v12
	s_add_u32 s0, s100, s0
	v_lshlrev_b32_e32 v106, 2, v7
	v_cndmask_b32_e32 v7, v210, v212, vcc
	v_mad_i64_i32 v[10:11], s[4:5], v14, s90, v[10:11]
	v_lshlrev_b64 v[12:13], 10, v[12:13]
	s_addc_u32 s1, s101, s1
	v_lshlrev_b64 v[14:15], 12, v[14:15]
	v_lshlrev_b32_e32 v107, 2, v7
	v_lshl_add_u64 v[12:13], s[0:1], 0, v[12:13]
	v_lshl_add_u64 v[14:15], s[2:3], 0, v[14:15]
	s_mov_b32 s2, -8
	s_waitcnt vmcnt(1)
	v_mov_b32_e32 v5, v4
	s_waitcnt vmcnt(0)
	v_mov_b32_e32 v9, v0
	v_and_b32_e32 v0, 63, v6
	v_mov_b32_e32 v7, v2
	v_lshlrev_b32_e32 v174, 3, v0
